# fix phase SGU position mixing: the four weight fragments of a column group requested up front, each k-step's eight LDS fragment reads batched (was load-wait per k-step and read-wait-MFMA per fragment)
# speedup vs baseline: 1.0004x; 1.0004x over previous
; __device__ __forceinline__ void phase_fix(KP kp, int l, unsigned char* shm) {
;     ...
;       for (int g = 0; g < 4; ++g) {
;         f32x4 acc[8];
; #pragma unroll
;         for (int db = 0; db < 8; ++db) acc[db] = (f32x4){0.f, 0.f, 0.f, 0.f};
; #pragma unroll
;         for (int ks = 0; ks < 4; ++ks) {
;           if (ks * 32 <= 16 * w + 15) {
;             const bf16x8 wf = *(const bf16x8*)(WSM + ((size_t)g * 128 + t) * 128 + ks * 32 + kg * 8);
; #pragma unroll
;             for (int db = 0; db < 8; ++db) {
;               const bf16x8 vf = *(const bf16x8*)(vnT + (size_t)(g * 128 + db * 16 + tl) * 136 + ks * 32 + kg * 8);
;               acc[db] = __builtin_amdgcn_mfma_f32_16x16x32_bf16(vf, wf, acc[db], 0, 0, 0);
;             }
;           }
;         }
.LBB0_2822:
	v_mov_b32_e32 v16, v17
	v_mov_b32_e32 v18, v17
	v_mov_b32_e32 v19, v17
	v_mov_b64_e32 v[0:1], v[16:17]
	v_mov_b64_e32 v[4:5], v[16:17]
	v_mov_b64_e32 v[8:9], v[16:17]
	v_mov_b64_e32 v[12:13], v[16:17]
	v_mov_b64_e32 v[22:23], v[18:19]
	v_mov_b64_e32 v[26:27], v[18:19]
	v_mov_b64_e32 v[30:31], v[18:19]
	v_mov_b64_e32 v[34:35], v[18:19]
	v_lshl_add_u64 v[62:63], s[14:15], 0, v[60:61]
	global_load_dwordx4 v[200:203], v[62:63], off offset:-128
	global_load_dwordx4 v[204:207], v[62:63], off offset:-64
	global_load_dwordx4 v[208:211], v[62:63], off
	global_load_dwordx4 v[212:215], v[62:63], off offset:64
	v_add_u32_e32 v51, s24, v43
	v_mov_b64_e32 v[2:3], v[18:19]
	v_mov_b64_e32 v[6:7], v[18:19]
	v_mov_b64_e32 v[10:11], v[18:19]
	v_mov_b64_e32 v[14:15], v[18:19]
	v_mov_b64_e32 v[20:21], v[16:17]
	v_mov_b64_e32 v[24:25], v[16:17]
	v_mov_b64_e32 v[28:29], v[16:17]
	v_mov_b64_e32 v[32:33], v[16:17]
	s_and_saveexec_b64 s[22:23], s[2:3]
	s_cbranch_execz .Lfixmm_chk1
	ds_read_b128 v[96:99], v51
	ds_read_b128 v[100:103], v51 offset:4352
	ds_read_b128 v[104:107], v51 offset:8704
	ds_read_b128 v[108:111], v51 offset:13056
	ds_read_b128 v[112:115], v51 offset:17408
	ds_read_b128 v[116:119], v51 offset:21760
	ds_read_b128 v[120:123], v51 offset:26112
	ds_read_b128 v[124:127], v51 offset:30464
	s_waitcnt vmcnt(3)
	s_waitcnt lgkmcnt(7)
	v_mfma_f32_16x16x32_bf16 v[32:35], v[96:99], v[200:203], 0
	s_waitcnt lgkmcnt(6)
	v_mfma_f32_16x16x32_bf16 v[28:31], v[100:103], v[200:203], 0
	s_waitcnt lgkmcnt(5)
	v_mfma_f32_16x16x32_bf16 v[24:27], v[104:107], v[200:203], 0
	s_waitcnt lgkmcnt(4)
	v_mfma_f32_16x16x32_bf16 v[20:23], v[108:111], v[200:203], 0
	s_waitcnt lgkmcnt(3)
	v_mfma_f32_16x16x32_bf16 v[12:15], v[112:115], v[200:203], 0
	s_waitcnt lgkmcnt(2)
	v_mfma_f32_16x16x32_bf16 v[8:11], v[116:119], v[200:203], 0
	s_waitcnt lgkmcnt(1)
	v_mfma_f32_16x16x32_bf16 v[4:7], v[120:123], v[200:203], 0
	s_waitcnt lgkmcnt(0)
	v_mfma_f32_16x16x32_bf16 v[0:3], v[124:127], v[200:203], 0
.Lfixmm_chk1:
	s_or_b64 exec, exec, s[22:23]
	s_and_saveexec_b64 s[22:23], s[4:5]
	s_cbranch_execz .Lfixmm_chk2
	ds_read_b128 v[96:99], v51 offset:64
	ds_read_b128 v[100:103], v51 offset:4416
	ds_read_b128 v[104:107], v51 offset:8768
	ds_read_b128 v[108:111], v51 offset:13120
	ds_read_b128 v[112:115], v51 offset:17472
	ds_read_b128 v[116:119], v51 offset:21824
	ds_read_b128 v[120:123], v51 offset:26176
	ds_read_b128 v[124:127], v51 offset:30528
	s_waitcnt vmcnt(2)
	s_waitcnt lgkmcnt(7)
	v_mfma_f32_16x16x32_bf16 v[32:35], v[96:99], v[204:207], v[32:35]
	s_waitcnt lgkmcnt(6)
	v_mfma_f32_16x16x32_bf16 v[28:31], v[100:103], v[204:207], v[28:31]
	s_waitcnt lgkmcnt(5)
	v_mfma_f32_16x16x32_bf16 v[24:27], v[104:107], v[204:207], v[24:27]
	s_waitcnt lgkmcnt(4)
	v_mfma_f32_16x16x32_bf16 v[20:23], v[108:111], v[204:207], v[20:23]
	s_waitcnt lgkmcnt(3)
	v_mfma_f32_16x16x32_bf16 v[12:15], v[112:115], v[204:207], v[12:15]
	s_waitcnt lgkmcnt(2)
	v_mfma_f32_16x16x32_bf16 v[8:11], v[116:119], v[204:207], v[8:11]
	s_waitcnt lgkmcnt(1)
	v_mfma_f32_16x16x32_bf16 v[4:7], v[120:123], v[204:207], v[4:7]
	s_waitcnt lgkmcnt(0)
	v_mfma_f32_16x16x32_bf16 v[0:3], v[124:127], v[204:207], v[0:3]
.Lfixmm_chk2:
	s_or_b64 exec, exec, s[22:23]
	s_and_saveexec_b64 s[22:23], s[6:7]
	s_cbranch_execz .Lfixmm_chk3
	ds_read_b128 v[96:99], v51 offset:128
	ds_read_b128 v[100:103], v51 offset:4480
	ds_read_b128 v[104:107], v51 offset:8832
	ds_read_b128 v[108:111], v51 offset:13184
	ds_read_b128 v[112:115], v51 offset:17536
	ds_read_b128 v[116:119], v51 offset:21888
	ds_read_b128 v[120:123], v51 offset:26240
	ds_read_b128 v[124:127], v51 offset:30592
	s_waitcnt vmcnt(1)
	s_waitcnt lgkmcnt(7)
	v_mfma_f32_16x16x32_bf16 v[32:35], v[96:99], v[208:211], v[32:35]
	s_waitcnt lgkmcnt(6)
	v_mfma_f32_16x16x32_bf16 v[28:31], v[100:103], v[208:211], v[28:31]
	s_waitcnt lgkmcnt(5)
	v_mfma_f32_16x16x32_bf16 v[24:27], v[104:107], v[208:211], v[24:27]
	s_waitcnt lgkmcnt(4)
	v_mfma_f32_16x16x32_bf16 v[20:23], v[108:111], v[208:211], v[20:23]
	s_waitcnt lgkmcnt(3)
	v_mfma_f32_16x16x32_bf16 v[12:15], v[112:115], v[208:211], v[12:15]
	s_waitcnt lgkmcnt(2)
	v_mfma_f32_16x16x32_bf16 v[8:11], v[116:119], v[208:211], v[8:11]
	s_waitcnt lgkmcnt(1)
	v_mfma_f32_16x16x32_bf16 v[4:7], v[120:123], v[208:211], v[4:7]
	s_waitcnt lgkmcnt(0)
	v_mfma_f32_16x16x32_bf16 v[0:3], v[124:127], v[208:211], v[0:3]
.Lfixmm_chk3:
	s_or_b64 exec, exec, s[22:23]
	s_and_saveexec_b64 s[22:23], s[8:9]
	s_cbranch_execz .LBB0_2821
	ds_read_b128 v[96:99], v51 offset:192
	ds_read_b128 v[100:103], v51 offset:4544
	ds_read_b128 v[104:107], v51 offset:8896
	ds_read_b128 v[108:111], v51 offset:13248
	ds_read_b128 v[112:115], v51 offset:17600
	ds_read_b128 v[116:119], v51 offset:21952
	ds_read_b128 v[120:123], v51 offset:26304
	ds_read_b128 v[124:127], v51 offset:30656
	s_waitcnt vmcnt(0)
	s_waitcnt lgkmcnt(7)
	v_mfma_f32_16x16x32_bf16 v[32:35], v[96:99], v[212:215], v[32:35]
	s_waitcnt lgkmcnt(6)
	v_mfma_f32_16x16x32_bf16 v[28:31], v[100:103], v[212:215], v[28:31]
	s_waitcnt lgkmcnt(5)
	v_mfma_f32_16x16x32_bf16 v[24:27], v[104:107], v[212:215], v[24:27]
	s_waitcnt lgkmcnt(4)
	v_mfma_f32_16x16x32_bf16 v[20:23], v[108:111], v[212:215], v[20:23]
	s_waitcnt lgkmcnt(3)
	v_mfma_f32_16x16x32_bf16 v[12:15], v[112:115], v[212:215], v[12:15]
	s_waitcnt lgkmcnt(2)
	v_mfma_f32_16x16x32_bf16 v[8:11], v[116:119], v[212:215], v[8:11]
	s_waitcnt lgkmcnt(1)
	v_mfma_f32_16x16x32_bf16 v[4:7], v[120:123], v[212:215], v[4:7]
	s_waitcnt lgkmcnt(0)
	v_mfma_f32_16x16x32_bf16 v[0:3], v[124:127], v[212:215], v[0:3]
	s_branch .LBB0_2821
